# v36 plus grid barrier, leaders only: no-return add on the top counter and poll it (k*nx) instead of returning atomic plus top-generation word; per-XCC generation relay unchanged
# speedup vs baseline: 1.0179x; 1.0177x over previous
.LBB0_111:
	s_andn2_saveexec_b64 s[0:1], s[20:21]
	s_cbranch_execz .LBB0_131
	s_mov_b64 s[4:5], exec
	buffer_wbl2 sc1
	s_waitcnt lgkmcnt(0)
	s_waitcnt vmcnt(0)
	v_mov_b32_e32 v3, 0x7400
	v_mov_b32_e32 v4, 1
	global_atomic_add v3, v4, s[54:55]
	v_mov_b32_e32 v2, 0x21164
	ds_read_b32 v2, v2
	s_waitcnt lgkmcnt(0)
	v_mul_u32_u24_e32 v2, 1, v2
	s_nop 0
	v_readfirstlane_b32 s98, v2
	s_mov_b32 s99, 0
.Lgb3_1_spin:
	global_load_dword v4, v3, s[54:55] sc1
	s_waitcnt vmcnt(0)
	v_readfirstlane_b32 s100, v4
	s_cmp_ge_u32 s100, s98
	s_cbranch_scc1 .Lgb3_1_done
	s_add_i32 s99, s99, 1
	s_cmp_gt_u32 s99, 0x40000
	s_cbranch_scc1 .Lgb3_1_done
	s_sleep 1
	s_branch .Lgb3_1_spin
.Lgb3_1_done:
	s_mov_b64 s[20:21], exec

.LBB0_252:
	s_andn2_saveexec_b64 s[0:1], s[12:13]
	s_cbranch_execz .LBB0_272
	s_mov_b64 s[4:5], exec
	buffer_wbl2 sc1
	s_waitcnt lgkmcnt(0)
	s_waitcnt vmcnt(0)
	v_mov_b32_e32 v3, 0x7400
	v_mov_b32_e32 v4, 1
	global_atomic_add v3, v4, s[54:55]
	v_mov_b32_e32 v2, 0x21164
	ds_read_b32 v2, v2
	s_waitcnt lgkmcnt(0)
	v_mul_u32_u24_e32 v2, 2, v2
	s_nop 0
	v_readfirstlane_b32 s98, v2
	s_mov_b32 s99, 0

.Lgb3_2_done:
	s_mov_b64 s[12:13], exec

.LBB0_340:
	s_andn2_saveexec_b64 s[0:1], s[14:15]
	s_cbranch_execz .LBB0_360
	s_mov_b64 s[4:5], exec
	buffer_wbl2 sc1
	s_waitcnt lgkmcnt(0)
	s_waitcnt vmcnt(0)
	v_mov_b32_e32 v3, 0x7400
	v_mov_b32_e32 v4, 1
	global_atomic_add v3, v4, s[54:55]
	v_mov_b32_e32 v2, 0x21164
	ds_read_b32 v2, v2
	s_waitcnt lgkmcnt(0)
	v_mul_u32_u24_e32 v2, 3, v2
	s_nop 0
	v_readfirstlane_b32 s98, v2
	s_mov_b32 s99, 0

.Lgb3_3_done:
	s_mov_b64 s[14:15], exec

.LBB0_422:
	s_andn2_saveexec_b64 s[0:1], s[10:11]
	s_cbranch_execz .LBB0_442
	s_mov_b64 s[4:5], exec
	buffer_wbl2 sc1
	s_waitcnt lgkmcnt(0)
	s_waitcnt vmcnt(0)
	v_mov_b32_e32 v3, 0x7400
	v_mov_b32_e32 v4, 1
	global_atomic_add v3, v4, s[54:55]
	v_mov_b32_e32 v2, 0x21164
	ds_read_b32 v2, v2
	s_waitcnt lgkmcnt(0)
	v_mul_u32_u24_e32 v2, 4, v2
	s_nop 0
	v_readfirstlane_b32 s98, v2
	s_mov_b32 s99, 0

.Lgb3_4_done:
	s_mov_b64 s[10:11], exec

.LBB0_552:
	s_andn2_saveexec_b64 s[0:1], s[16:17]
	s_cbranch_execz .LBB0_572
	s_mov_b64 s[4:5], exec
	buffer_wbl2 sc1
	s_waitcnt lgkmcnt(0)
	s_waitcnt vmcnt(0)
	v_mov_b32_e32 v3, 0x7400
	v_mov_b32_e32 v4, 1
	global_atomic_add v3, v4, s[54:55]
	v_mov_b32_e32 v2, 0x21164
	ds_read_b32 v2, v2
	s_waitcnt lgkmcnt(0)
	v_mul_u32_u24_e32 v2, 5, v2
	s_nop 0
	v_readfirstlane_b32 s98, v2
	s_mov_b32 s99, 0

.Lgb3_5_done:
	s_mov_b64 s[16:17], exec

.LBB0_620:
	s_andn2_saveexec_b64 s[4:5], s[10:11]
	s_cbranch_execz .LBB0_640
	s_mov_b64 s[4:5], exec
	buffer_wbl2 sc1
	s_waitcnt lgkmcnt(0)
	s_waitcnt vmcnt(0)
	v_mov_b32_e32 v3, 0x7400
	v_mov_b32_e32 v4, 1
	global_atomic_add v3, v4, s[54:55]
	v_mov_b32_e32 v2, 0x21164
	ds_read_b32 v2, v2
	s_waitcnt lgkmcnt(0)
	v_mul_u32_u24_e32 v2, 6, v2
	s_nop 0
	v_readfirstlane_b32 s98, v2
	s_mov_b32 s99, 0
